# retention: all six LDS-DMAs of a region issued in its VALU-only tail (after the P store, before the V fragment prefetch)
# speedup vs baseline: 1.0419x; 1.0022x over previous
; #define RET_BAR() do { asm volatile("s_waitcnt lgkmcnt(0)" ::: "memory"); __builtin_amdgcn_s_barrier(); asm volatile("" ::: "memory"); } while (0)
; #define RET_LOADV(t) do { RET_KV(t) const char* vb_ = kb_ + (1024 + h * 256) * 2; const unsigned lo_ = (unsigned)(tid >> 6) * kp_ + (unsigned)(tid & 63) * 16u; \
;         _Pragma("unroll") for (int i_ = 0; i_ < 8; ++i_) vr[i_] = *(const u32x4*)(vb_ + (size_t)(8u * i_) * kp_ + lo_); } while (0)
; #define RET_STOREV() do { _Pragma("unroll") for (int i_ = 0; i_ < 8; ++i_) *(LAS u32x4*)(Vs + ((tid >> 6) + 8 * i_) * 1040 + (tid & 63) * 16) = vr[i_]; } while (0)
; __device__ __forceinline__ void ret_unit(ldsp lds, bf16_t* R, const bf16_t* RC, int b, int h, int qblk, float lgf2, float lgb2, const int tid_in) {
;     ...
;     for (int t = 0; t < 36; ++t) {
;         int tl_ = tid_outer; asm volatile("" : "+v"(tl_));
;         const int tid = tl_, lane = tid & 63, l15 = lane & 15, lg = lane >> 4;
;         if (wid < 4) { RET_PV(t); if (t + 1 < 36) RET_S(t + 1, TI(t + 1)); }
;         else { if (t + 1 < 36) RET_S(t + 1, TI(t + 1)); RET_PV(t); }
;         RET_BAR();
;         asm volatile("s_waitcnt vmcnt(0)" ::: "memory");
;         if (t + 1 < 36) RET_STOREV();
;         if (t + 2 < 36) RET_LOADV(TI(t + 2));
;         if (t + 3 < 36) RET_DMAK(TI(t + 3), (t + 1) & 1);
;         RET_BAR();
.Lret_loop:
	s_cmp_eq_u32 s38, 0
	s_cbranch_scc0 .Lret_regY_7
	ds_read_b128 v[102:105], v182 offset:16384
	ds_read_b128 v[106:109], v246 offset:16384
	ds_read_b128 v[110:113], v247 offset:16384
	ds_read_b128 v[114:117], v248 offset:16384
	ds_read_b128 v[118:121], v182 offset:16640
	ds_read_b128 v[122:125], v246 offset:16640
	ds_read_b128 v[126:129], v247 offset:16640
	ds_read_b128 v[130:133], v248 offset:16640
	ds_read_b128 v[134:137], v187 offset:0
	ds_read_b128 v[138:141], v187 offset:1280
	ds_read_b128 v[142:145], v187 offset:2560
	ds_read_b128 v[146:149], v187 offset:3840
	s_waitcnt lgkmcnt(11)
	v_mfma_f32_16x16x32_bf16 v[98:101], v[102:105], v[64:67], 0
	s_waitcnt lgkmcnt(10)
	v_mfma_f32_16x16x32_bf16 v[98:101], v[106:109], v[68:71], v[98:101]
	s_waitcnt lgkmcnt(9)
	v_mfma_f32_16x16x32_bf16 v[98:101], v[110:113], v[72:75], v[98:101]
	s_waitcnt lgkmcnt(8)
	v_mfma_f32_16x16x32_bf16 v[98:101], v[114:117], v[76:79], v[98:101]
	s_waitcnt lgkmcnt(7)
	v_mfma_f32_16x16x32_bf16 v[98:101], v[118:121], v[80:83], v[98:101]
	s_waitcnt lgkmcnt(6)
	v_mfma_f32_16x16x32_bf16 v[98:101], v[122:125], v[84:87], v[98:101]
	s_waitcnt lgkmcnt(5)
	v_mfma_f32_16x16x32_bf16 v[98:101], v[126:129], v[88:91], v[98:101]
	s_waitcnt lgkmcnt(4)
	v_mfma_f32_16x16x32_bf16 v[98:101], v[130:133], v[92:95], v[98:101]
	s_waitcnt lgkmcnt(0)
	v_mfma_f32_16x16x32_bf16 v[0:3], v[150:153], v[134:137], v[0:3]
	v_mfma_f32_16x16x32_bf16 v[16:19], v[154:157], v[134:137], v[16:19]
	v_mfma_f32_16x16x32_bf16 v[32:35], v[158:161], v[134:137], v[32:35]
	v_mfma_f32_16x16x32_bf16 v[48:51], v[162:165], v[134:137], v[48:51]
	v_mfma_f32_16x16x32_bf16 v[4:7], v[150:153], v[138:141], v[4:7]
	v_mfma_f32_16x16x32_bf16 v[20:23], v[154:157], v[138:141], v[20:23]
	v_mfma_f32_16x16x32_bf16 v[36:39], v[158:161], v[138:141], v[36:39]
	v_mfma_f32_16x16x32_bf16 v[52:55], v[162:165], v[138:141], v[52:55]
	v_mfma_f32_16x16x32_bf16 v[8:11], v[150:153], v[142:145], v[8:11]
	v_mfma_f32_16x16x32_bf16 v[24:27], v[154:157], v[142:145], v[24:27]
	v_mfma_f32_16x16x32_bf16 v[40:43], v[158:161], v[142:145], v[40:43]
	v_mfma_f32_16x16x32_bf16 v[56:59], v[162:165], v[142:145], v[56:59]
	v_mfma_f32_16x16x32_bf16 v[12:15], v[150:153], v[146:149], v[12:15]
	v_mfma_f32_16x16x32_bf16 v[28:31], v[154:157], v[146:149], v[28:31]
	v_mfma_f32_16x16x32_bf16 v[44:47], v[158:161], v[146:149], v[44:47]
	v_mfma_f32_16x16x32_bf16 v[60:63], v[162:165], v[146:149], v[60:63]
	v_mul_f32_e32 v170, v98, v242
	v_mul_f32_e32 v171, v99, v243
	v_mul_f32_e32 v172, v100, v244
	v_mul_f32_e32 v173, v101, v245
	v_cvt_pk_bf16_f32 v174, v170, v171
	v_cvt_pk_bf16_f32 v175, v172, v173
	ds_write_b64 v188, v[174:175] offset:5120
	s_waitcnt vmcnt(4)
	s_add_i32 s41, s27, 1
	v_readlane_b32 s42, v240, s41
	v_readlane_b32 s43, v241, s41
	v_readlane_b32 s4, v237, s41
	s_mov_b32 s5, s4
	s_nop 0
	v_cndmask_b32_e64 v230, v191, v189, s[4:5]
	v_cndmask_b32_e64 v231, v192, v190, s[4:5]
	v_cndmask_b32_e64 v232, v198, v193, s[4:5]
	v_cndmask_b32_e64 v233, v199, v194, s[4:5]
	v_cndmask_b32_e64 v234, v200, v195, s[4:5]
	v_cndmask_b32_e64 v235, v202, v197, s[4:5]
	s_add_i32 m0, s54, 0
	s_nop 0
	global_load_lds_dwordx4 v230, s[42:43]
	s_add_i32 m0, s54, 1024
	s_nop 0
	global_load_lds_dwordx4 v231, s[42:43]
	s_add_i32 m0, s55, 0
	s_nop 0
	global_load_lds_dwordx4 v232, s[42:43]
	s_add_i32 m0, s55, 1024
	s_nop 0
	global_load_lds_dwordx4 v233, s[42:43]
	s_add_i32 m0, s55, 2048
	s_nop 0
	global_load_lds_dwordx4 v234, s[42:43]
	s_add_i32 m0, s55, 3072
	s_nop 0
	global_load_lds_dwordx4 v235, s[42:43]
	ds_read_b64_tr_b16 v[150:151], v183 offset:4096
	ds_read_b64_tr_b16 v[152:153], v183 offset:4608
	ds_read_b64_tr_b16 v[154:155], v184 offset:4096
	ds_read_b64_tr_b16 v[156:157], v184 offset:4608
	ds_read_b64_tr_b16 v[158:159], v185 offset:4096
	ds_read_b64_tr_b16 v[160:161], v185 offset:4608
	ds_read_b64_tr_b16 v[162:163], v186 offset:4096
	ds_read_b64_tr_b16 v[164:165], v186 offset:4608
	s_add_i32 s41, s27, 1
	v_readlane_b32 s37, v236, s41
	s_cmp_lt_u32 s37, 32
	s_cbranch_scc0 .Lret_wctx_9
	s_lshl_b32 s100, s37, 6
	s_cmp_eq_u32 s37, s9
	s_cbranch_scc1 .Lret_wdiag_10
	s_cmp_lt_u32 s37, s9
	s_cselect_b32 s101, s11, s12
	v_subrev_u32_e32 v170, s100, v203
	v_subrev_u32_e32 v171, s100, v204
	v_subrev_u32_e32 v172, s100, v205
	v_subrev_u32_e32 v173, s100, v206
	v_cvt_f32_i32_e32 v174, v170
	v_cvt_f32_i32_e32 v175, v171
	v_cvt_f32_i32_e32 v176, v172
	v_cvt_f32_i32_e32 v177, v173
	v_mul_f32_e64 v178, s101, |v174|
	v_mul_f32_e64 v179, s101, |v175|
	v_mul_f32_e64 v180, s101, |v176|
	v_mul_f32_e64 v181, s101, |v177|
	v_exp_f32_e32 v166, v178
	v_exp_f32_e32 v167, v179
	v_exp_f32_e32 v168, v180
	v_exp_f32_e32 v169, v181
	s_branch .Lret_wdone_11

; #define RET_BAR() do { asm volatile("s_waitcnt lgkmcnt(0)" ::: "memory"); __builtin_amdgcn_s_barrier(); asm volatile("" ::: "memory"); } while (0)
; #define RET_LOADV(t) do { RET_KV(t) const char* vb_ = kb_ + (1024 + h * 256) * 2; const unsigned lo_ = (unsigned)(tid >> 6) * kp_ + (unsigned)(tid & 63) * 16u; \
;         _Pragma("unroll") for (int i_ = 0; i_ < 8; ++i_) vr[i_] = *(const u32x4*)(vb_ + (size_t)(8u * i_) * kp_ + lo_); } while (0)
; #define RET_STOREV() do { _Pragma("unroll") for (int i_ = 0; i_ < 8; ++i_) *(LAS u32x4*)(Vs + ((tid >> 6) + 8 * i_) * 1040 + (tid & 63) * 16) = vr[i_]; } while (0)
; __device__ __forceinline__ void ret_unit(ldsp lds, bf16_t* R, const bf16_t* RC, int b, int h, int qblk, float lgf2, float lgb2, const int tid_in) {
;     ...
;     for (int t = 0; t < 36; ++t) {
;         int tl_ = tid_outer; asm volatile("" : "+v"(tl_));
;         const int tid = tl_, lane = tid & 63, l15 = lane & 15, lg = lane >> 4;
;         if (wid < 4) { RET_PV(t); if (t + 1 < 36) RET_S(t + 1, TI(t + 1)); }
;         else { if (t + 1 < 36) RET_S(t + 1, TI(t + 1)); RET_PV(t); }
;         RET_BAR();
;         asm volatile("s_waitcnt vmcnt(0)" ::: "memory");
;         if (t + 1 < 36) RET_STOREV();
;         if (t + 2 < 36) RET_LOADV(TI(t + 2));
;         if (t + 3 < 36) RET_DMAK(TI(t + 3), (t + 1) & 1);
;         RET_BAR();
.Lret_wdone_14:
	v_mul_f32_e32 v170, v98, v242
	v_mul_f32_e32 v171, v99, v243
	v_mul_f32_e32 v172, v100, v244
	v_mul_f32_e32 v173, v101, v245
	v_cvt_pk_bf16_f32 v174, v170, v171
	v_cvt_pk_bf16_f32 v175, v172, v173
	ds_write_b64 v188, v[174:175] offset:5120
	s_waitcnt vmcnt(4)
	s_add_i32 s41, s27, 1
	v_readlane_b32 s42, v240, s41
	v_readlane_b32 s43, v241, s41
	v_readlane_b32 s4, v237, s41
	s_mov_b32 s5, s4
	s_nop 0
	v_cndmask_b32_e64 v230, v191, v189, s[4:5]
	v_cndmask_b32_e64 v231, v192, v190, s[4:5]
	v_cndmask_b32_e64 v232, v198, v193, s[4:5]
	v_cndmask_b32_e64 v233, v199, v194, s[4:5]
	v_cndmask_b32_e64 v234, v200, v195, s[4:5]
	v_cndmask_b32_e64 v235, v202, v197, s[4:5]
	s_add_i32 m0, s54, 0
	s_nop 0
	global_load_lds_dwordx4 v230, s[42:43]
	s_add_i32 m0, s54, 1024
	s_nop 0
	global_load_lds_dwordx4 v231, s[42:43]
	s_add_i32 m0, s55, 0
	s_nop 0
	global_load_lds_dwordx4 v232, s[42:43]
	s_add_i32 m0, s55, 1024
	s_nop 0
	global_load_lds_dwordx4 v233, s[42:43]
	s_add_i32 m0, s55, 2048
	s_nop 0
	global_load_lds_dwordx4 v234, s[42:43]
	s_add_i32 m0, s55, 3072
	s_nop 0
	global_load_lds_dwordx4 v235, s[42:43]
	ds_read_b64_tr_b16 v[150:151], v183 offset:4096
	ds_read_b64_tr_b16 v[152:153], v183 offset:4608
	ds_read_b64_tr_b16 v[154:155], v184 offset:4096
	ds_read_b64_tr_b16 v[156:157], v184 offset:4608
	ds_read_b64_tr_b16 v[158:159], v185 offset:4096
	ds_read_b64_tr_b16 v[160:161], v185 offset:4608
	ds_read_b64_tr_b16 v[162:163], v186 offset:4096
	ds_read_b64_tr_b16 v[164:165], v186 offset:4608
	s_waitcnt lgkmcnt(8)
.Lret_regJ_8:
	s_barrier
	s_cmp_eq_u32 s38, 0
	s_cbranch_scc0 .Lret_regY_15
	ds_read_b128 v[102:105], v182 offset:32768
	ds_read_b128 v[106:109], v246 offset:32768
	ds_read_b128 v[110:113], v247 offset:32768
	ds_read_b128 v[114:117], v248 offset:32768
	ds_read_b128 v[118:121], v182 offset:33024
	ds_read_b128 v[122:125], v246 offset:33024
	ds_read_b128 v[126:129], v247 offset:33024
	ds_read_b128 v[130:133], v248 offset:33024
	ds_read_b128 v[134:137], v187 offset:5120
	ds_read_b128 v[138:141], v187 offset:6400
	ds_read_b128 v[142:145], v187 offset:7680
	ds_read_b128 v[146:149], v187 offset:8960
	s_waitcnt lgkmcnt(11)
	v_mfma_f32_16x16x32_bf16 v[98:101], v[102:105], v[64:67], 0
	s_waitcnt lgkmcnt(10)
	v_mfma_f32_16x16x32_bf16 v[98:101], v[106:109], v[68:71], v[98:101]
	s_waitcnt lgkmcnt(9)
	v_mfma_f32_16x16x32_bf16 v[98:101], v[110:113], v[72:75], v[98:101]
	s_waitcnt lgkmcnt(8)
	v_mfma_f32_16x16x32_bf16 v[98:101], v[114:117], v[76:79], v[98:101]
	s_waitcnt lgkmcnt(7)
	v_mfma_f32_16x16x32_bf16 v[98:101], v[118:121], v[80:83], v[98:101]
	s_waitcnt lgkmcnt(6)
	v_mfma_f32_16x16x32_bf16 v[98:101], v[122:125], v[84:87], v[98:101]
	s_waitcnt lgkmcnt(5)
	v_mfma_f32_16x16x32_bf16 v[98:101], v[126:129], v[88:91], v[98:101]
	s_waitcnt lgkmcnt(4)
	v_mfma_f32_16x16x32_bf16 v[98:101], v[130:133], v[92:95], v[98:101]
	s_waitcnt lgkmcnt(0)
	v_mfma_f32_16x16x32_bf16 v[0:3], v[150:153], v[134:137], v[0:3]
	v_mfma_f32_16x16x32_bf16 v[16:19], v[154:157], v[134:137], v[16:19]
	v_mfma_f32_16x16x32_bf16 v[32:35], v[158:161], v[134:137], v[32:35]
	v_mfma_f32_16x16x32_bf16 v[48:51], v[162:165], v[134:137], v[48:51]
	v_mfma_f32_16x16x32_bf16 v[4:7], v[150:153], v[138:141], v[4:7]
	v_mfma_f32_16x16x32_bf16 v[20:23], v[154:157], v[138:141], v[20:23]
	v_mfma_f32_16x16x32_bf16 v[36:39], v[158:161], v[138:141], v[36:39]
	v_mfma_f32_16x16x32_bf16 v[52:55], v[162:165], v[138:141], v[52:55]
	v_mfma_f32_16x16x32_bf16 v[8:11], v[150:153], v[142:145], v[8:11]
	v_mfma_f32_16x16x32_bf16 v[24:27], v[154:157], v[142:145], v[24:27]
	v_mfma_f32_16x16x32_bf16 v[40:43], v[158:161], v[142:145], v[40:43]
	v_mfma_f32_16x16x32_bf16 v[56:59], v[162:165], v[142:145], v[56:59]
	v_mfma_f32_16x16x32_bf16 v[12:15], v[150:153], v[146:149], v[12:15]
	v_mfma_f32_16x16x32_bf16 v[28:31], v[154:157], v[146:149], v[28:31]
	v_mfma_f32_16x16x32_bf16 v[44:47], v[158:161], v[146:149], v[44:47]
	v_mfma_f32_16x16x32_bf16 v[60:63], v[162:165], v[146:149], v[60:63]
	v_mul_f32_e32 v170, v98, v166
	v_mul_f32_e32 v171, v99, v167
	v_mul_f32_e32 v172, v100, v168
	v_mul_f32_e32 v173, v101, v169
	v_cvt_pk_bf16_f32 v174, v170, v171
	v_cvt_pk_bf16_f32 v175, v172, v173
	ds_write_b64 v188, v[174:175] offset:0
	s_waitcnt vmcnt(4)
	s_add_i32 s41, s27, 2
	v_readlane_b32 s42, v238, s41
	v_readlane_b32 s43, v239, s41
	v_readlane_b32 s4, v237, s41
	s_mov_b32 s5, s4
	s_nop 0
	v_cndmask_b32_e64 v230, v191, v189, s[4:5]
	v_cndmask_b32_e64 v231, v192, v190, s[4:5]
	v_cndmask_b32_e64 v232, v198, v193, s[4:5]
	v_cndmask_b32_e64 v233, v199, v194, s[4:5]
	v_cndmask_b32_e64 v234, v200, v195, s[4:5]
	v_cndmask_b32_e64 v235, v202, v197, s[4:5]
	s_add_i32 m0, s54, 16384
	s_nop 0
	global_load_lds_dwordx4 v230, s[42:43]
	s_add_i32 m0, s54, 17408
	s_nop 0
	global_load_lds_dwordx4 v231, s[42:43]
	s_add_i32 m0, s55, 4096
	s_nop 0
	global_load_lds_dwordx4 v232, s[42:43]
	s_add_i32 m0, s55, 5120
	s_nop 0
	global_load_lds_dwordx4 v233, s[42:43]
	s_add_i32 m0, s55, 6144
	s_nop 0
	global_load_lds_dwordx4 v234, s[42:43]
	s_add_i32 m0, s55, 7168
	s_nop 0
	global_load_lds_dwordx4 v235, s[42:43]
	ds_read_b64_tr_b16 v[150:151], v183 offset:8192
	ds_read_b64_tr_b16 v[152:153], v183 offset:8704
	ds_read_b64_tr_b16 v[154:155], v184 offset:8192
	ds_read_b64_tr_b16 v[156:157], v184 offset:8704
	ds_read_b64_tr_b16 v[158:159], v185 offset:8192
	ds_read_b64_tr_b16 v[160:161], v185 offset:8704
	ds_read_b64_tr_b16 v[162:163], v186 offset:8192
	ds_read_b64_tr_b16 v[164:165], v186 offset:8704
	s_add_i32 s41, s27, 1
	v_readlane_b32 s37, v236, s41
	s_cmp_lt_u32 s37, 32
	s_cbranch_scc0 .Lret_wctx_17
	s_lshl_b32 s100, s37, 6
	s_add_i32 s100, s100, 32
	s_cmp_eq_u32 s37, s9
	s_cbranch_scc1 .Lret_wdiag_18
	s_cmp_lt_u32 s37, s9
	s_cselect_b32 s101, s11, s12
	v_subrev_u32_e32 v170, s100, v203
	v_subrev_u32_e32 v171, s100, v204
	v_subrev_u32_e32 v172, s100, v205
	v_subrev_u32_e32 v173, s100, v206
	v_cvt_f32_i32_e32 v174, v170
	v_cvt_f32_i32_e32 v175, v171
	v_cvt_f32_i32_e32 v176, v172
	v_cvt_f32_i32_e32 v177, v173
	v_mul_f32_e64 v178, s101, |v174|
	v_mul_f32_e64 v179, s101, |v175|
	v_mul_f32_e64 v180, s101, |v176|
	v_mul_f32_e64 v181, s101, |v177|
	v_exp_f32_e32 v242, v178
	v_exp_f32_e32 v243, v179
	v_exp_f32_e32 v244, v180
	v_exp_f32_e32 v245, v181
	s_branch .Lret_wdone_19

; #define RET_BAR() do { asm volatile("s_waitcnt lgkmcnt(0)" ::: "memory"); __builtin_amdgcn_s_barrier(); asm volatile("" ::: "memory"); } while (0)
; #define RET_LOADV(t) do { RET_KV(t) const char* vb_ = kb_ + (1024 + h * 256) * 2; const unsigned lo_ = (unsigned)(tid >> 6) * kp_ + (unsigned)(tid & 63) * 16u; \
;         _Pragma("unroll") for (int i_ = 0; i_ < 8; ++i_) vr[i_] = *(const u32x4*)(vb_ + (size_t)(8u * i_) * kp_ + lo_); } while (0)
; #define RET_STOREV() do { _Pragma("unroll") for (int i_ = 0; i_ < 8; ++i_) *(LAS u32x4*)(Vs + ((tid >> 6) + 8 * i_) * 1040 + (tid & 63) * 16) = vr[i_]; } while (0)
; __device__ __forceinline__ void ret_unit(ldsp lds, bf16_t* R, const bf16_t* RC, int b, int h, int qblk, float lgf2, float lgb2, const int tid_in) {
;     ...
;     for (int t = 0; t < 36; ++t) {
;         int tl_ = tid_outer; asm volatile("" : "+v"(tl_));
;         const int tid = tl_, lane = tid & 63, l15 = lane & 15, lg = lane >> 4;
;         if (wid < 4) { RET_PV(t); if (t + 1 < 36) RET_S(t + 1, TI(t + 1)); }
;         else { if (t + 1 < 36) RET_S(t + 1, TI(t + 1)); RET_PV(t); }
;         RET_BAR();
;         asm volatile("s_waitcnt vmcnt(0)" ::: "memory");
;         if (t + 1 < 36) RET_STOREV();
;         if (t + 2 < 36) RET_LOADV(TI(t + 2));
;         if (t + 3 < 36) RET_DMAK(TI(t + 3), (t + 1) & 1);
;         RET_BAR();
.Lret_wdone_22:
	v_mul_f32_e32 v170, v98, v166
	v_mul_f32_e32 v171, v99, v167
	v_mul_f32_e32 v172, v100, v168
	v_mul_f32_e32 v173, v101, v169
	v_cvt_pk_bf16_f32 v174, v170, v171
	v_cvt_pk_bf16_f32 v175, v172, v173
	ds_write_b64 v188, v[174:175] offset:0
	s_waitcnt vmcnt(4)
	s_add_i32 s41, s27, 2
	v_readlane_b32 s42, v238, s41
	v_readlane_b32 s43, v239, s41
	v_readlane_b32 s4, v237, s41
	s_mov_b32 s5, s4
	s_nop 0
	v_cndmask_b32_e64 v230, v191, v189, s[4:5]
	v_cndmask_b32_e64 v231, v192, v190, s[4:5]
	v_cndmask_b32_e64 v232, v198, v193, s[4:5]
	v_cndmask_b32_e64 v233, v199, v194, s[4:5]
	v_cndmask_b32_e64 v234, v200, v195, s[4:5]
	v_cndmask_b32_e64 v235, v202, v197, s[4:5]
	s_add_i32 m0, s54, 16384
	s_nop 0
	global_load_lds_dwordx4 v230, s[42:43]
	s_add_i32 m0, s54, 17408
	s_nop 0
	global_load_lds_dwordx4 v231, s[42:43]
	s_add_i32 m0, s55, 4096
	s_nop 0
	global_load_lds_dwordx4 v232, s[42:43]
	s_add_i32 m0, s55, 5120
	s_nop 0
	global_load_lds_dwordx4 v233, s[42:43]
	s_add_i32 m0, s55, 6144
	s_nop 0
	global_load_lds_dwordx4 v234, s[42:43]
	s_add_i32 m0, s55, 7168
	s_nop 0
	global_load_lds_dwordx4 v235, s[42:43]
	ds_read_b64_tr_b16 v[150:151], v183 offset:8192
	ds_read_b64_tr_b16 v[152:153], v183 offset:8704
	ds_read_b64_tr_b16 v[154:155], v184 offset:8192
	ds_read_b64_tr_b16 v[156:157], v184 offset:8704
	ds_read_b64_tr_b16 v[158:159], v185 offset:8192
	ds_read_b64_tr_b16 v[160:161], v185 offset:8704
	ds_read_b64_tr_b16 v[162:163], v186 offset:8192
	ds_read_b64_tr_b16 v[164:165], v186 offset:8704
	s_waitcnt lgkmcnt(8)
.Lret_regJ_16:
	s_barrier
	s_cmp_eq_u32 s38, 0
	s_cbranch_scc0 .Lret_regY_23
	ds_read_b128 v[102:105], v182 offset:0
	ds_read_b128 v[106:109], v246 offset:0
	ds_read_b128 v[110:113], v247 offset:0
	ds_read_b128 v[114:117], v248 offset:0
	ds_read_b128 v[118:121], v182 offset:256
	ds_read_b128 v[122:125], v246 offset:256
	ds_read_b128 v[126:129], v247 offset:256
	ds_read_b128 v[130:133], v248 offset:256
	ds_read_b128 v[134:137], v187 offset:0
	ds_read_b128 v[138:141], v187 offset:1280
	ds_read_b128 v[142:145], v187 offset:2560
	ds_read_b128 v[146:149], v187 offset:3840
	s_waitcnt lgkmcnt(11)
	v_mfma_f32_16x16x32_bf16 v[98:101], v[102:105], v[64:67], 0
	s_waitcnt lgkmcnt(10)
	v_mfma_f32_16x16x32_bf16 v[98:101], v[106:109], v[68:71], v[98:101]
	s_waitcnt lgkmcnt(9)
	v_mfma_f32_16x16x32_bf16 v[98:101], v[110:113], v[72:75], v[98:101]
	s_waitcnt lgkmcnt(8)
	v_mfma_f32_16x16x32_bf16 v[98:101], v[114:117], v[76:79], v[98:101]
	s_waitcnt lgkmcnt(7)
	v_mfma_f32_16x16x32_bf16 v[98:101], v[118:121], v[80:83], v[98:101]
	s_waitcnt lgkmcnt(6)
	v_mfma_f32_16x16x32_bf16 v[98:101], v[122:125], v[84:87], v[98:101]
	s_waitcnt lgkmcnt(5)
	v_mfma_f32_16x16x32_bf16 v[98:101], v[126:129], v[88:91], v[98:101]
	s_waitcnt lgkmcnt(4)
	v_mfma_f32_16x16x32_bf16 v[98:101], v[130:133], v[92:95], v[98:101]
	s_waitcnt lgkmcnt(0)
	v_mfma_f32_16x16x32_bf16 v[0:3], v[150:153], v[134:137], v[0:3]
	v_mfma_f32_16x16x32_bf16 v[16:19], v[154:157], v[134:137], v[16:19]
	v_mfma_f32_16x16x32_bf16 v[32:35], v[158:161], v[134:137], v[32:35]
	v_mfma_f32_16x16x32_bf16 v[48:51], v[162:165], v[134:137], v[48:51]
	v_mfma_f32_16x16x32_bf16 v[4:7], v[150:153], v[138:141], v[4:7]
	v_mfma_f32_16x16x32_bf16 v[20:23], v[154:157], v[138:141], v[20:23]
	v_mfma_f32_16x16x32_bf16 v[36:39], v[158:161], v[138:141], v[36:39]
	v_mfma_f32_16x16x32_bf16 v[52:55], v[162:165], v[138:141], v[52:55]
	v_mfma_f32_16x16x32_bf16 v[8:11], v[150:153], v[142:145], v[8:11]
	v_mfma_f32_16x16x32_bf16 v[24:27], v[154:157], v[142:145], v[24:27]
	v_mfma_f32_16x16x32_bf16 v[40:43], v[158:161], v[142:145], v[40:43]
	v_mfma_f32_16x16x32_bf16 v[56:59], v[162:165], v[142:145], v[56:59]
	v_mfma_f32_16x16x32_bf16 v[12:15], v[150:153], v[146:149], v[12:15]
	v_mfma_f32_16x16x32_bf16 v[28:31], v[154:157], v[146:149], v[28:31]
	v_mfma_f32_16x16x32_bf16 v[44:47], v[158:161], v[146:149], v[44:47]
	v_mfma_f32_16x16x32_bf16 v[60:63], v[162:165], v[146:149], v[60:63]
	v_mul_f32_e32 v170, v98, v242
	v_mul_f32_e32 v171, v99, v243
	v_mul_f32_e32 v172, v100, v244
	v_mul_f32_e32 v173, v101, v245
	v_cvt_pk_bf16_f32 v174, v170, v171
	v_cvt_pk_bf16_f32 v175, v172, v173
	ds_write_b64 v188, v[174:175] offset:5120
	s_waitcnt vmcnt(4)
	s_add_i32 s41, s27, 2
	v_readlane_b32 s42, v240, s41
	v_readlane_b32 s43, v241, s41
	v_readlane_b32 s4, v237, s41
	s_mov_b32 s5, s4
	s_nop 0
	v_cndmask_b32_e64 v230, v191, v189, s[4:5]
	v_cndmask_b32_e64 v231, v192, v190, s[4:5]
	v_cndmask_b32_e64 v232, v198, v193, s[4:5]
	v_cndmask_b32_e64 v233, v199, v194, s[4:5]
	v_cndmask_b32_e64 v234, v200, v195, s[4:5]
	v_cndmask_b32_e64 v235, v202, v197, s[4:5]
	s_add_i32 m0, s54, 32768
	s_nop 0
	global_load_lds_dwordx4 v230, s[42:43]
	s_add_i32 m0, s54, 33792
	s_nop 0
	global_load_lds_dwordx4 v231, s[42:43]
	s_add_i32 m0, s55, 8192
	s_nop 0
	global_load_lds_dwordx4 v232, s[42:43]
	s_add_i32 m0, s55, 9216
	s_nop 0
	global_load_lds_dwordx4 v233, s[42:43]
	s_add_i32 m0, s55, 10240
	s_nop 0
	global_load_lds_dwordx4 v234, s[42:43]
	s_add_i32 m0, s55, 11264
	s_nop 0
	global_load_lds_dwordx4 v235, s[42:43]
	ds_read_b64_tr_b16 v[150:151], v183 offset:0
	ds_read_b64_tr_b16 v[152:153], v183 offset:512
	ds_read_b64_tr_b16 v[154:155], v184 offset:0
	ds_read_b64_tr_b16 v[156:157], v184 offset:512
	ds_read_b64_tr_b16 v[158:159], v185 offset:0
	ds_read_b64_tr_b16 v[160:161], v185 offset:512
	ds_read_b64_tr_b16 v[162:163], v186 offset:0
	ds_read_b64_tr_b16 v[164:165], v186 offset:512
	s_add_i32 s41, s27, 2
	v_readlane_b32 s37, v236, s41
	s_cmp_lt_u32 s37, 32
	s_cbranch_scc0 .Lret_wctx_25
	s_lshl_b32 s100, s37, 6
	s_cmp_eq_u32 s37, s9
	s_cbranch_scc1 .Lret_wdiag_26
	s_cmp_lt_u32 s37, s9
	s_cselect_b32 s101, s11, s12
	v_subrev_u32_e32 v170, s100, v203
	v_subrev_u32_e32 v171, s100, v204
	v_subrev_u32_e32 v172, s100, v205
	v_subrev_u32_e32 v173, s100, v206
	v_cvt_f32_i32_e32 v174, v170
	v_cvt_f32_i32_e32 v175, v171
	v_cvt_f32_i32_e32 v176, v172
	v_cvt_f32_i32_e32 v177, v173
	v_mul_f32_e64 v178, s101, |v174|
	v_mul_f32_e64 v179, s101, |v175|
	v_mul_f32_e64 v180, s101, |v176|
	v_mul_f32_e64 v181, s101, |v177|
	v_exp_f32_e32 v166, v178
	v_exp_f32_e32 v167, v179
	v_exp_f32_e32 v168, v180
	v_exp_f32_e32 v169, v181
	s_branch .Lret_wdone_27

; #define RET_BAR() do { asm volatile("s_waitcnt lgkmcnt(0)" ::: "memory"); __builtin_amdgcn_s_barrier(); asm volatile("" ::: "memory"); } while (0)
; #define RET_LOADV(t) do { RET_KV(t) const char* vb_ = kb_ + (1024 + h * 256) * 2; const unsigned lo_ = (unsigned)(tid >> 6) * kp_ + (unsigned)(tid & 63) * 16u; \
;         _Pragma("unroll") for (int i_ = 0; i_ < 8; ++i_) vr[i_] = *(const u32x4*)(vb_ + (size_t)(8u * i_) * kp_ + lo_); } while (0)
; #define RET_STOREV() do { _Pragma("unroll") for (int i_ = 0; i_ < 8; ++i_) *(LAS u32x4*)(Vs + ((tid >> 6) + 8 * i_) * 1040 + (tid & 63) * 16) = vr[i_]; } while (0)
; __device__ __forceinline__ void ret_unit(ldsp lds, bf16_t* R, const bf16_t* RC, int b, int h, int qblk, float lgf2, float lgb2, const int tid_in) {
;     ...
;     for (int t = 0; t < 36; ++t) {
;         int tl_ = tid_outer; asm volatile("" : "+v"(tl_));
;         const int tid = tl_, lane = tid & 63, l15 = lane & 15, lg = lane >> 4;
;         if (wid < 4) { RET_PV(t); if (t + 1 < 36) RET_S(t + 1, TI(t + 1)); }
;         else { if (t + 1 < 36) RET_S(t + 1, TI(t + 1)); RET_PV(t); }
;         RET_BAR();
;         asm volatile("s_waitcnt vmcnt(0)" ::: "memory");
;         if (t + 1 < 36) RET_STOREV();
;         if (t + 2 < 36) RET_LOADV(TI(t + 2));
;         if (t + 3 < 36) RET_DMAK(TI(t + 3), (t + 1) & 1);
;         RET_BAR();
.Lret_wdone_30:
	v_mul_f32_e32 v170, v98, v242
	v_mul_f32_e32 v171, v99, v243
	v_mul_f32_e32 v172, v100, v244
	v_mul_f32_e32 v173, v101, v245
	v_cvt_pk_bf16_f32 v174, v170, v171
	v_cvt_pk_bf16_f32 v175, v172, v173
	ds_write_b64 v188, v[174:175] offset:5120
	s_waitcnt vmcnt(4)
	s_add_i32 s41, s27, 2
	v_readlane_b32 s42, v240, s41
	v_readlane_b32 s43, v241, s41
	v_readlane_b32 s4, v237, s41
	s_mov_b32 s5, s4
	s_nop 0
	v_cndmask_b32_e64 v230, v191, v189, s[4:5]
	v_cndmask_b32_e64 v231, v192, v190, s[4:5]
	v_cndmask_b32_e64 v232, v198, v193, s[4:5]
	v_cndmask_b32_e64 v233, v199, v194, s[4:5]
	v_cndmask_b32_e64 v234, v200, v195, s[4:5]
	v_cndmask_b32_e64 v235, v202, v197, s[4:5]
	s_add_i32 m0, s54, 32768
	s_nop 0
	global_load_lds_dwordx4 v230, s[42:43]
	s_add_i32 m0, s54, 33792
	s_nop 0
	global_load_lds_dwordx4 v231, s[42:43]
	s_add_i32 m0, s55, 8192
	s_nop 0
	global_load_lds_dwordx4 v232, s[42:43]
	s_add_i32 m0, s55, 9216
	s_nop 0
	global_load_lds_dwordx4 v233, s[42:43]
	s_add_i32 m0, s55, 10240
	s_nop 0
	global_load_lds_dwordx4 v234, s[42:43]
	s_add_i32 m0, s55, 11264
	s_nop 0
	global_load_lds_dwordx4 v235, s[42:43]
	ds_read_b64_tr_b16 v[150:151], v183 offset:0
	ds_read_b64_tr_b16 v[152:153], v183 offset:512
	ds_read_b64_tr_b16 v[154:155], v184 offset:0
	ds_read_b64_tr_b16 v[156:157], v184 offset:512
	ds_read_b64_tr_b16 v[158:159], v185 offset:0
	ds_read_b64_tr_b16 v[160:161], v185 offset:512
	ds_read_b64_tr_b16 v[162:163], v186 offset:0
	ds_read_b64_tr_b16 v[164:165], v186 offset:512
	s_waitcnt lgkmcnt(8)
.Lret_regJ_24:
	s_barrier
	s_cmp_eq_u32 s38, 0
	s_cbranch_scc0 .Lret_regY_31
	ds_read_b128 v[102:105], v182 offset:16384
	ds_read_b128 v[106:109], v246 offset:16384
	ds_read_b128 v[110:113], v247 offset:16384
	ds_read_b128 v[114:117], v248 offset:16384
	ds_read_b128 v[118:121], v182 offset:16640
	ds_read_b128 v[122:125], v246 offset:16640
	ds_read_b128 v[126:129], v247 offset:16640
	ds_read_b128 v[130:133], v248 offset:16640
	ds_read_b128 v[134:137], v187 offset:5120
	ds_read_b128 v[138:141], v187 offset:6400
	ds_read_b128 v[142:145], v187 offset:7680
	ds_read_b128 v[146:149], v187 offset:8960
	s_waitcnt lgkmcnt(11)
	v_mfma_f32_16x16x32_bf16 v[98:101], v[102:105], v[64:67], 0
	s_waitcnt lgkmcnt(10)
	v_mfma_f32_16x16x32_bf16 v[98:101], v[106:109], v[68:71], v[98:101]
	s_waitcnt lgkmcnt(9)
	v_mfma_f32_16x16x32_bf16 v[98:101], v[110:113], v[72:75], v[98:101]
	s_waitcnt lgkmcnt(8)
	v_mfma_f32_16x16x32_bf16 v[98:101], v[114:117], v[76:79], v[98:101]
	s_waitcnt lgkmcnt(7)
	v_mfma_f32_16x16x32_bf16 v[98:101], v[118:121], v[80:83], v[98:101]
	s_waitcnt lgkmcnt(6)
	v_mfma_f32_16x16x32_bf16 v[98:101], v[122:125], v[84:87], v[98:101]
	s_waitcnt lgkmcnt(5)
	v_mfma_f32_16x16x32_bf16 v[98:101], v[126:129], v[88:91], v[98:101]
	s_waitcnt lgkmcnt(4)
	v_mfma_f32_16x16x32_bf16 v[98:101], v[130:133], v[92:95], v[98:101]
	s_waitcnt lgkmcnt(0)
	v_mfma_f32_16x16x32_bf16 v[0:3], v[150:153], v[134:137], v[0:3]
	v_mfma_f32_16x16x32_bf16 v[16:19], v[154:157], v[134:137], v[16:19]
	v_mfma_f32_16x16x32_bf16 v[32:35], v[158:161], v[134:137], v[32:35]
	v_mfma_f32_16x16x32_bf16 v[48:51], v[162:165], v[134:137], v[48:51]
	v_mfma_f32_16x16x32_bf16 v[4:7], v[150:153], v[138:141], v[4:7]
	v_mfma_f32_16x16x32_bf16 v[20:23], v[154:157], v[138:141], v[20:23]
	v_mfma_f32_16x16x32_bf16 v[36:39], v[158:161], v[138:141], v[36:39]
	v_mfma_f32_16x16x32_bf16 v[52:55], v[162:165], v[138:141], v[52:55]
	v_mfma_f32_16x16x32_bf16 v[8:11], v[150:153], v[142:145], v[8:11]
	v_mfma_f32_16x16x32_bf16 v[24:27], v[154:157], v[142:145], v[24:27]
	v_mfma_f32_16x16x32_bf16 v[40:43], v[158:161], v[142:145], v[40:43]
	v_mfma_f32_16x16x32_bf16 v[56:59], v[162:165], v[142:145], v[56:59]
	v_mfma_f32_16x16x32_bf16 v[12:15], v[150:153], v[146:149], v[12:15]
	v_mfma_f32_16x16x32_bf16 v[28:31], v[154:157], v[146:149], v[28:31]
	v_mfma_f32_16x16x32_bf16 v[44:47], v[158:161], v[146:149], v[44:47]
	v_mfma_f32_16x16x32_bf16 v[60:63], v[162:165], v[146:149], v[60:63]
	v_mul_f32_e32 v170, v98, v166
	v_mul_f32_e32 v171, v99, v167
	v_mul_f32_e32 v172, v100, v168
	v_mul_f32_e32 v173, v101, v169
	v_cvt_pk_bf16_f32 v174, v170, v171
	v_cvt_pk_bf16_f32 v175, v172, v173
	ds_write_b64 v188, v[174:175] offset:0
	s_waitcnt vmcnt(4)
	s_add_i32 s41, s27, 3
	v_readlane_b32 s42, v238, s41
	v_readlane_b32 s43, v239, s41
	v_readlane_b32 s4, v237, s41
	s_mov_b32 s5, s4
	s_nop 0
	v_cndmask_b32_e64 v230, v191, v189, s[4:5]
	v_cndmask_b32_e64 v231, v192, v190, s[4:5]
	v_cndmask_b32_e64 v232, v198, v193, s[4:5]
	v_cndmask_b32_e64 v233, v199, v194, s[4:5]
	v_cndmask_b32_e64 v234, v200, v195, s[4:5]
	v_cndmask_b32_e64 v235, v202, v197, s[4:5]
	s_add_i32 m0, s54, 0
	s_nop 0
	global_load_lds_dwordx4 v230, s[42:43]
	s_add_i32 m0, s54, 1024
	s_nop 0
	global_load_lds_dwordx4 v231, s[42:43]
	s_add_i32 m0, s55, 0
	s_nop 0
	global_load_lds_dwordx4 v232, s[42:43]
	s_add_i32 m0, s55, 1024
	s_nop 0
	global_load_lds_dwordx4 v233, s[42:43]
	s_add_i32 m0, s55, 2048
	s_nop 0
	global_load_lds_dwordx4 v234, s[42:43]
	s_add_i32 m0, s55, 3072
	s_nop 0
	global_load_lds_dwordx4 v235, s[42:43]
	ds_read_b64_tr_b16 v[150:151], v183 offset:4096
	ds_read_b64_tr_b16 v[152:153], v183 offset:4608
	ds_read_b64_tr_b16 v[154:155], v184 offset:4096
	ds_read_b64_tr_b16 v[156:157], v184 offset:4608
	ds_read_b64_tr_b16 v[158:159], v185 offset:4096
	ds_read_b64_tr_b16 v[160:161], v185 offset:4608
	ds_read_b64_tr_b16 v[162:163], v186 offset:4096
	ds_read_b64_tr_b16 v[164:165], v186 offset:4608
	s_add_i32 s41, s27, 2
	v_readlane_b32 s37, v236, s41
	s_cmp_lt_u32 s37, 32
	s_cbranch_scc0 .Lret_wctx_33
	s_lshl_b32 s100, s37, 6
	s_add_i32 s100, s100, 32
	s_cmp_eq_u32 s37, s9
	s_cbranch_scc1 .Lret_wdiag_34
	s_cmp_lt_u32 s37, s9
	s_cselect_b32 s101, s11, s12
	v_subrev_u32_e32 v170, s100, v203
	v_subrev_u32_e32 v171, s100, v204
	v_subrev_u32_e32 v172, s100, v205
	v_subrev_u32_e32 v173, s100, v206
	v_cvt_f32_i32_e32 v174, v170
	v_cvt_f32_i32_e32 v175, v171
	v_cvt_f32_i32_e32 v176, v172
	v_cvt_f32_i32_e32 v177, v173
	v_mul_f32_e64 v178, s101, |v174|
	v_mul_f32_e64 v179, s101, |v175|
	v_mul_f32_e64 v180, s101, |v176|
	v_mul_f32_e64 v181, s101, |v177|
	v_exp_f32_e32 v242, v178
	v_exp_f32_e32 v243, v179
	v_exp_f32_e32 v244, v180
	v_exp_f32_e32 v245, v181
	s_branch .Lret_wdone_35

; #define RET_BAR() do { asm volatile("s_waitcnt lgkmcnt(0)" ::: "memory"); __builtin_amdgcn_s_barrier(); asm volatile("" ::: "memory"); } while (0)
; #define RET_LOADV(t) do { RET_KV(t) const char* vb_ = kb_ + (1024 + h * 256) * 2; const unsigned lo_ = (unsigned)(tid >> 6) * kp_ + (unsigned)(tid & 63) * 16u; \
;         _Pragma("unroll") for (int i_ = 0; i_ < 8; ++i_) vr[i_] = *(const u32x4*)(vb_ + (size_t)(8u * i_) * kp_ + lo_); } while (0)
; #define RET_STOREV() do { _Pragma("unroll") for (int i_ = 0; i_ < 8; ++i_) *(LAS u32x4*)(Vs + ((tid >> 6) + 8 * i_) * 1040 + (tid & 63) * 16) = vr[i_]; } while (0)
; __device__ __forceinline__ void ret_unit(ldsp lds, bf16_t* R, const bf16_t* RC, int b, int h, int qblk, float lgf2, float lgb2, const int tid_in) {
;     ...
;     for (int t = 0; t < 36; ++t) {
;         int tl_ = tid_outer; asm volatile("" : "+v"(tl_));
;         const int tid = tl_, lane = tid & 63, l15 = lane & 15, lg = lane >> 4;
;         if (wid < 4) { RET_PV(t); if (t + 1 < 36) RET_S(t + 1, TI(t + 1)); }
;         else { if (t + 1 < 36) RET_S(t + 1, TI(t + 1)); RET_PV(t); }
;         RET_BAR();
;         asm volatile("s_waitcnt vmcnt(0)" ::: "memory");
;         if (t + 1 < 36) RET_STOREV();
;         if (t + 2 < 36) RET_LOADV(TI(t + 2));
;         if (t + 3 < 36) RET_DMAK(TI(t + 3), (t + 1) & 1);
;         RET_BAR();
.Lret_wdone_38:
	v_mul_f32_e32 v170, v98, v166
	v_mul_f32_e32 v171, v99, v167
	v_mul_f32_e32 v172, v100, v168
	v_mul_f32_e32 v173, v101, v169
	v_cvt_pk_bf16_f32 v174, v170, v171
	v_cvt_pk_bf16_f32 v175, v172, v173
	ds_write_b64 v188, v[174:175] offset:0
	s_waitcnt vmcnt(4)
	s_add_i32 s41, s27, 3
	v_readlane_b32 s42, v238, s41
	v_readlane_b32 s43, v239, s41
	v_readlane_b32 s4, v237, s41
	s_mov_b32 s5, s4
	s_nop 0
	v_cndmask_b32_e64 v230, v191, v189, s[4:5]
	v_cndmask_b32_e64 v231, v192, v190, s[4:5]
	v_cndmask_b32_e64 v232, v198, v193, s[4:5]
	v_cndmask_b32_e64 v233, v199, v194, s[4:5]
	v_cndmask_b32_e64 v234, v200, v195, s[4:5]
	v_cndmask_b32_e64 v235, v202, v197, s[4:5]
	s_add_i32 m0, s54, 0
	s_nop 0
	global_load_lds_dwordx4 v230, s[42:43]
	s_add_i32 m0, s54, 1024
	s_nop 0
	global_load_lds_dwordx4 v231, s[42:43]
	s_add_i32 m0, s55, 0
	s_nop 0
	global_load_lds_dwordx4 v232, s[42:43]
	s_add_i32 m0, s55, 1024
	s_nop 0
	global_load_lds_dwordx4 v233, s[42:43]
	s_add_i32 m0, s55, 2048
	s_nop 0
	global_load_lds_dwordx4 v234, s[42:43]
	s_add_i32 m0, s55, 3072
	s_nop 0
	global_load_lds_dwordx4 v235, s[42:43]
	ds_read_b64_tr_b16 v[150:151], v183 offset:4096
	ds_read_b64_tr_b16 v[152:153], v183 offset:4608
	ds_read_b64_tr_b16 v[154:155], v184 offset:4096
	ds_read_b64_tr_b16 v[156:157], v184 offset:4608
	ds_read_b64_tr_b16 v[158:159], v185 offset:4096
	ds_read_b64_tr_b16 v[160:161], v185 offset:4608
	ds_read_b64_tr_b16 v[162:163], v186 offset:4096
	ds_read_b64_tr_b16 v[164:165], v186 offset:4608
	s_waitcnt lgkmcnt(8)
.Lret_regJ_32:
	s_barrier
	s_cmp_eq_u32 s38, 0
	s_cbranch_scc0 .Lret_regY_39
	ds_read_b128 v[102:105], v182 offset:32768
	ds_read_b128 v[106:109], v246 offset:32768
	ds_read_b128 v[110:113], v247 offset:32768
	ds_read_b128 v[114:117], v248 offset:32768
	ds_read_b128 v[118:121], v182 offset:33024
	ds_read_b128 v[122:125], v246 offset:33024
	ds_read_b128 v[126:129], v247 offset:33024
	ds_read_b128 v[130:133], v248 offset:33024
	ds_read_b128 v[134:137], v187 offset:0
	ds_read_b128 v[138:141], v187 offset:1280
	ds_read_b128 v[142:145], v187 offset:2560
	ds_read_b128 v[146:149], v187 offset:3840
	s_waitcnt lgkmcnt(11)
	v_mfma_f32_16x16x32_bf16 v[98:101], v[102:105], v[64:67], 0
	s_waitcnt lgkmcnt(10)
	v_mfma_f32_16x16x32_bf16 v[98:101], v[106:109], v[68:71], v[98:101]
	s_waitcnt lgkmcnt(9)
	v_mfma_f32_16x16x32_bf16 v[98:101], v[110:113], v[72:75], v[98:101]
	s_waitcnt lgkmcnt(8)
	v_mfma_f32_16x16x32_bf16 v[98:101], v[114:117], v[76:79], v[98:101]
	s_waitcnt lgkmcnt(7)
	v_mfma_f32_16x16x32_bf16 v[98:101], v[118:121], v[80:83], v[98:101]
	s_waitcnt lgkmcnt(6)
	v_mfma_f32_16x16x32_bf16 v[98:101], v[122:125], v[84:87], v[98:101]
	s_waitcnt lgkmcnt(5)
	v_mfma_f32_16x16x32_bf16 v[98:101], v[126:129], v[88:91], v[98:101]
	s_waitcnt lgkmcnt(4)
	v_mfma_f32_16x16x32_bf16 v[98:101], v[130:133], v[92:95], v[98:101]
	s_waitcnt lgkmcnt(0)
	v_mfma_f32_16x16x32_bf16 v[0:3], v[150:153], v[134:137], v[0:3]
	v_mfma_f32_16x16x32_bf16 v[16:19], v[154:157], v[134:137], v[16:19]
	v_mfma_f32_16x16x32_bf16 v[32:35], v[158:161], v[134:137], v[32:35]
	v_mfma_f32_16x16x32_bf16 v[48:51], v[162:165], v[134:137], v[48:51]
	v_mfma_f32_16x16x32_bf16 v[4:7], v[150:153], v[138:141], v[4:7]
	v_mfma_f32_16x16x32_bf16 v[20:23], v[154:157], v[138:141], v[20:23]
	v_mfma_f32_16x16x32_bf16 v[36:39], v[158:161], v[138:141], v[36:39]
	v_mfma_f32_16x16x32_bf16 v[52:55], v[162:165], v[138:141], v[52:55]
	v_mfma_f32_16x16x32_bf16 v[8:11], v[150:153], v[142:145], v[8:11]
	v_mfma_f32_16x16x32_bf16 v[24:27], v[154:157], v[142:145], v[24:27]
	v_mfma_f32_16x16x32_bf16 v[40:43], v[158:161], v[142:145], v[40:43]
	v_mfma_f32_16x16x32_bf16 v[56:59], v[162:165], v[142:145], v[56:59]
	v_mfma_f32_16x16x32_bf16 v[12:15], v[150:153], v[146:149], v[12:15]
	v_mfma_f32_16x16x32_bf16 v[28:31], v[154:157], v[146:149], v[28:31]
	v_mfma_f32_16x16x32_bf16 v[44:47], v[158:161], v[146:149], v[44:47]
	v_mfma_f32_16x16x32_bf16 v[60:63], v[162:165], v[146:149], v[60:63]
	v_mul_f32_e32 v170, v98, v242
	v_mul_f32_e32 v171, v99, v243
	v_mul_f32_e32 v172, v100, v244
	v_mul_f32_e32 v173, v101, v245
	v_cvt_pk_bf16_f32 v174, v170, v171
	v_cvt_pk_bf16_f32 v175, v172, v173
	ds_write_b64 v188, v[174:175] offset:5120
	s_waitcnt vmcnt(4)
	s_add_i32 s41, s27, 3
	v_readlane_b32 s42, v240, s41
	v_readlane_b32 s43, v241, s41
	v_readlane_b32 s4, v237, s41
	s_mov_b32 s5, s4
	s_nop 0
	v_cndmask_b32_e64 v230, v191, v189, s[4:5]
	v_cndmask_b32_e64 v231, v192, v190, s[4:5]
	v_cndmask_b32_e64 v232, v198, v193, s[4:5]
	v_cndmask_b32_e64 v233, v199, v194, s[4:5]
	v_cndmask_b32_e64 v234, v200, v195, s[4:5]
	v_cndmask_b32_e64 v235, v202, v197, s[4:5]
	s_add_i32 m0, s54, 16384
	s_nop 0
	global_load_lds_dwordx4 v230, s[42:43]
	s_add_i32 m0, s54, 17408
	s_nop 0
	global_load_lds_dwordx4 v231, s[42:43]
	s_add_i32 m0, s55, 4096
	s_nop 0
	global_load_lds_dwordx4 v232, s[42:43]
	s_add_i32 m0, s55, 5120
	s_nop 0
	global_load_lds_dwordx4 v233, s[42:43]
	s_add_i32 m0, s55, 6144
	s_nop 0
	global_load_lds_dwordx4 v234, s[42:43]
	s_add_i32 m0, s55, 7168
	s_nop 0
	global_load_lds_dwordx4 v235, s[42:43]
	ds_read_b64_tr_b16 v[150:151], v183 offset:8192
	ds_read_b64_tr_b16 v[152:153], v183 offset:8704
	ds_read_b64_tr_b16 v[154:155], v184 offset:8192
	ds_read_b64_tr_b16 v[156:157], v184 offset:8704
	ds_read_b64_tr_b16 v[158:159], v185 offset:8192
	ds_read_b64_tr_b16 v[160:161], v185 offset:8704
	ds_read_b64_tr_b16 v[162:163], v186 offset:8192
	ds_read_b64_tr_b16 v[164:165], v186 offset:8704
	s_add_i32 s41, s27, 3
	v_readlane_b32 s37, v236, s41
	s_cmp_lt_u32 s37, 32
	s_cbranch_scc0 .Lret_wctx_41
	s_lshl_b32 s100, s37, 6
	s_cmp_eq_u32 s37, s9
	s_cbranch_scc1 .Lret_wdiag_42
	s_cmp_lt_u32 s37, s9
	s_cselect_b32 s101, s11, s12
	v_subrev_u32_e32 v170, s100, v203
	v_subrev_u32_e32 v171, s100, v204
	v_subrev_u32_e32 v172, s100, v205
	v_subrev_u32_e32 v173, s100, v206
	v_cvt_f32_i32_e32 v174, v170
	v_cvt_f32_i32_e32 v175, v171
	v_cvt_f32_i32_e32 v176, v172
	v_cvt_f32_i32_e32 v177, v173
	v_mul_f32_e64 v178, s101, |v174|
	v_mul_f32_e64 v179, s101, |v175|
	v_mul_f32_e64 v180, s101, |v176|
	v_mul_f32_e64 v181, s101, |v177|
	v_exp_f32_e32 v166, v178
	v_exp_f32_e32 v167, v179
	v_exp_f32_e32 v168, v180
	v_exp_f32_e32 v169, v181
	s_branch .Lret_wdone_43

; #define RET_BAR() do { asm volatile("s_waitcnt lgkmcnt(0)" ::: "memory"); __builtin_amdgcn_s_barrier(); asm volatile("" ::: "memory"); } while (0)
; #define RET_LOADV(t) do { RET_KV(t) const char* vb_ = kb_ + (1024 + h * 256) * 2; const unsigned lo_ = (unsigned)(tid >> 6) * kp_ + (unsigned)(tid & 63) * 16u; \
;         _Pragma("unroll") for (int i_ = 0; i_ < 8; ++i_) vr[i_] = *(const u32x4*)(vb_ + (size_t)(8u * i_) * kp_ + lo_); } while (0)
; #define RET_STOREV() do { _Pragma("unroll") for (int i_ = 0; i_ < 8; ++i_) *(LAS u32x4*)(Vs + ((tid >> 6) + 8 * i_) * 1040 + (tid & 63) * 16) = vr[i_]; } while (0)
; __device__ __forceinline__ void ret_unit(ldsp lds, bf16_t* R, const bf16_t* RC, int b, int h, int qblk, float lgf2, float lgb2, const int tid_in) {
;     ...
;     for (int t = 0; t < 36; ++t) {
;         int tl_ = tid_outer; asm volatile("" : "+v"(tl_));
;         const int tid = tl_, lane = tid & 63, l15 = lane & 15, lg = lane >> 4;
;         if (wid < 4) { RET_PV(t); if (t + 1 < 36) RET_S(t + 1, TI(t + 1)); }
;         else { if (t + 1 < 36) RET_S(t + 1, TI(t + 1)); RET_PV(t); }
;         RET_BAR();
;         asm volatile("s_waitcnt vmcnt(0)" ::: "memory");
;         if (t + 1 < 36) RET_STOREV();
;         if (t + 2 < 36) RET_LOADV(TI(t + 2));
;         if (t + 3 < 36) RET_DMAK(TI(t + 3), (t + 1) & 1);
;         RET_BAR();
.Lret_wdone_46:
	v_mul_f32_e32 v170, v98, v242
	v_mul_f32_e32 v171, v99, v243
	v_mul_f32_e32 v172, v100, v244
	v_mul_f32_e32 v173, v101, v245
	v_cvt_pk_bf16_f32 v174, v170, v171
	v_cvt_pk_bf16_f32 v175, v172, v173
	ds_write_b64 v188, v[174:175] offset:5120
	s_waitcnt vmcnt(4)
	s_add_i32 s41, s27, 3
	v_readlane_b32 s42, v240, s41
	v_readlane_b32 s43, v241, s41
	v_readlane_b32 s4, v237, s41
	s_mov_b32 s5, s4
	s_nop 0
	v_cndmask_b32_e64 v230, v191, v189, s[4:5]
	v_cndmask_b32_e64 v231, v192, v190, s[4:5]
	v_cndmask_b32_e64 v232, v198, v193, s[4:5]
	v_cndmask_b32_e64 v233, v199, v194, s[4:5]
	v_cndmask_b32_e64 v234, v200, v195, s[4:5]
	v_cndmask_b32_e64 v235, v202, v197, s[4:5]
	s_add_i32 m0, s54, 16384
	s_nop 0
	global_load_lds_dwordx4 v230, s[42:43]
	s_add_i32 m0, s54, 17408
	s_nop 0
	global_load_lds_dwordx4 v231, s[42:43]
	s_add_i32 m0, s55, 4096
	s_nop 0
	global_load_lds_dwordx4 v232, s[42:43]
	s_add_i32 m0, s55, 5120
	s_nop 0
	global_load_lds_dwordx4 v233, s[42:43]
	s_add_i32 m0, s55, 6144
	s_nop 0
	global_load_lds_dwordx4 v234, s[42:43]
	s_add_i32 m0, s55, 7168
	s_nop 0
	global_load_lds_dwordx4 v235, s[42:43]
	ds_read_b64_tr_b16 v[150:151], v183 offset:8192
	ds_read_b64_tr_b16 v[152:153], v183 offset:8704
	ds_read_b64_tr_b16 v[154:155], v184 offset:8192
	ds_read_b64_tr_b16 v[156:157], v184 offset:8704
	ds_read_b64_tr_b16 v[158:159], v185 offset:8192
	ds_read_b64_tr_b16 v[160:161], v185 offset:8704
	ds_read_b64_tr_b16 v[162:163], v186 offset:8192
	ds_read_b64_tr_b16 v[164:165], v186 offset:8704
	s_waitcnt lgkmcnt(8)
.Lret_regJ_40:
	s_barrier
	s_cmp_eq_u32 s38, 0
	s_cbranch_scc0 .Lret_regY_47
	ds_read_b128 v[102:105], v182 offset:0
	ds_read_b128 v[106:109], v246 offset:0
	ds_read_b128 v[110:113], v247 offset:0
	ds_read_b128 v[114:117], v248 offset:0
	ds_read_b128 v[118:121], v182 offset:256
	ds_read_b128 v[122:125], v246 offset:256
	ds_read_b128 v[126:129], v247 offset:256
	ds_read_b128 v[130:133], v248 offset:256
	ds_read_b128 v[134:137], v187 offset:5120
	ds_read_b128 v[138:141], v187 offset:6400
	ds_read_b128 v[142:145], v187 offset:7680
	ds_read_b128 v[146:149], v187 offset:8960
	s_waitcnt lgkmcnt(11)
	v_mfma_f32_16x16x32_bf16 v[98:101], v[102:105], v[64:67], 0
	s_waitcnt lgkmcnt(10)
	v_mfma_f32_16x16x32_bf16 v[98:101], v[106:109], v[68:71], v[98:101]
	s_waitcnt lgkmcnt(9)
	v_mfma_f32_16x16x32_bf16 v[98:101], v[110:113], v[72:75], v[98:101]
	s_waitcnt lgkmcnt(8)
	v_mfma_f32_16x16x32_bf16 v[98:101], v[114:117], v[76:79], v[98:101]
	s_waitcnt lgkmcnt(7)
	v_mfma_f32_16x16x32_bf16 v[98:101], v[118:121], v[80:83], v[98:101]
	s_waitcnt lgkmcnt(6)
	v_mfma_f32_16x16x32_bf16 v[98:101], v[122:125], v[84:87], v[98:101]
	s_waitcnt lgkmcnt(5)
	v_mfma_f32_16x16x32_bf16 v[98:101], v[126:129], v[88:91], v[98:101]
	s_waitcnt lgkmcnt(4)
	v_mfma_f32_16x16x32_bf16 v[98:101], v[130:133], v[92:95], v[98:101]
	s_waitcnt lgkmcnt(0)
	v_mfma_f32_16x16x32_bf16 v[0:3], v[150:153], v[134:137], v[0:3]
	v_mfma_f32_16x16x32_bf16 v[16:19], v[154:157], v[134:137], v[16:19]
	v_mfma_f32_16x16x32_bf16 v[32:35], v[158:161], v[134:137], v[32:35]
	v_mfma_f32_16x16x32_bf16 v[48:51], v[162:165], v[134:137], v[48:51]
	v_mfma_f32_16x16x32_bf16 v[4:7], v[150:153], v[138:141], v[4:7]
	v_mfma_f32_16x16x32_bf16 v[20:23], v[154:157], v[138:141], v[20:23]
	v_mfma_f32_16x16x32_bf16 v[36:39], v[158:161], v[138:141], v[36:39]
	v_mfma_f32_16x16x32_bf16 v[52:55], v[162:165], v[138:141], v[52:55]
	v_mfma_f32_16x16x32_bf16 v[8:11], v[150:153], v[142:145], v[8:11]
	v_mfma_f32_16x16x32_bf16 v[24:27], v[154:157], v[142:145], v[24:27]
	v_mfma_f32_16x16x32_bf16 v[40:43], v[158:161], v[142:145], v[40:43]
	v_mfma_f32_16x16x32_bf16 v[56:59], v[162:165], v[142:145], v[56:59]
	v_mfma_f32_16x16x32_bf16 v[12:15], v[150:153], v[146:149], v[12:15]
	v_mfma_f32_16x16x32_bf16 v[28:31], v[154:157], v[146:149], v[28:31]
	v_mfma_f32_16x16x32_bf16 v[44:47], v[158:161], v[146:149], v[44:47]
	v_mfma_f32_16x16x32_bf16 v[60:63], v[162:165], v[146:149], v[60:63]
	v_mul_f32_e32 v170, v98, v166
	v_mul_f32_e32 v171, v99, v167
	v_mul_f32_e32 v172, v100, v168
	v_mul_f32_e32 v173, v101, v169
	v_cvt_pk_bf16_f32 v174, v170, v171
	v_cvt_pk_bf16_f32 v175, v172, v173
	ds_write_b64 v188, v[174:175] offset:0
	s_waitcnt vmcnt(4)
	s_add_i32 s41, s27, 4
	v_readlane_b32 s42, v238, s41
	v_readlane_b32 s43, v239, s41
	v_readlane_b32 s4, v237, s41
	s_mov_b32 s5, s4
	s_nop 0
	v_cndmask_b32_e64 v230, v191, v189, s[4:5]
	v_cndmask_b32_e64 v231, v192, v190, s[4:5]
	v_cndmask_b32_e64 v232, v198, v193, s[4:5]
	v_cndmask_b32_e64 v233, v199, v194, s[4:5]
	v_cndmask_b32_e64 v234, v200, v195, s[4:5]
	v_cndmask_b32_e64 v235, v202, v197, s[4:5]
	s_add_i32 m0, s54, 32768
	s_nop 0
	global_load_lds_dwordx4 v230, s[42:43]
	s_add_i32 m0, s54, 33792
	s_nop 0
	global_load_lds_dwordx4 v231, s[42:43]
	s_add_i32 m0, s55, 8192
	s_nop 0
	global_load_lds_dwordx4 v232, s[42:43]
	s_add_i32 m0, s55, 9216
	s_nop 0
	global_load_lds_dwordx4 v233, s[42:43]
	s_add_i32 m0, s55, 10240
	s_nop 0
	global_load_lds_dwordx4 v234, s[42:43]
	s_add_i32 m0, s55, 11264
	s_nop 0
	global_load_lds_dwordx4 v235, s[42:43]
	ds_read_b64_tr_b16 v[150:151], v183 offset:0
	ds_read_b64_tr_b16 v[152:153], v183 offset:512
	ds_read_b64_tr_b16 v[154:155], v184 offset:0
	ds_read_b64_tr_b16 v[156:157], v184 offset:512
	ds_read_b64_tr_b16 v[158:159], v185 offset:0
	ds_read_b64_tr_b16 v[160:161], v185 offset:512
	ds_read_b64_tr_b16 v[162:163], v186 offset:0
	ds_read_b64_tr_b16 v[164:165], v186 offset:512
	s_add_i32 s41, s27, 3
	v_readlane_b32 s37, v236, s41
	s_cmp_lt_u32 s37, 32
	s_cbranch_scc0 .Lret_wctx_49
	s_lshl_b32 s100, s37, 6
	s_add_i32 s100, s100, 32
	s_cmp_eq_u32 s37, s9
	s_cbranch_scc1 .Lret_wdiag_50
	s_cmp_lt_u32 s37, s9
	s_cselect_b32 s101, s11, s12
	v_subrev_u32_e32 v170, s100, v203
	v_subrev_u32_e32 v171, s100, v204
	v_subrev_u32_e32 v172, s100, v205
	v_subrev_u32_e32 v173, s100, v206
	v_cvt_f32_i32_e32 v174, v170
	v_cvt_f32_i32_e32 v175, v171
	v_cvt_f32_i32_e32 v176, v172
	v_cvt_f32_i32_e32 v177, v173
	v_mul_f32_e64 v178, s101, |v174|
	v_mul_f32_e64 v179, s101, |v175|
	v_mul_f32_e64 v180, s101, |v176|
	v_mul_f32_e64 v181, s101, |v177|
	v_exp_f32_e32 v242, v178
	v_exp_f32_e32 v243, v179
	v_exp_f32_e32 v244, v180
	v_exp_f32_e32 v245, v181
	s_branch .Lret_wdone_51

; #define RET_BAR() do { asm volatile("s_waitcnt lgkmcnt(0)" ::: "memory"); __builtin_amdgcn_s_barrier(); asm volatile("" ::: "memory"); } while (0)
; #define RET_LOADV(t) do { RET_KV(t) const char* vb_ = kb_ + (1024 + h * 256) * 2; const unsigned lo_ = (unsigned)(tid >> 6) * kp_ + (unsigned)(tid & 63) * 16u; \
;         _Pragma("unroll") for (int i_ = 0; i_ < 8; ++i_) vr[i_] = *(const u32x4*)(vb_ + (size_t)(8u * i_) * kp_ + lo_); } while (0)
; #define RET_STOREV() do { _Pragma("unroll") for (int i_ = 0; i_ < 8; ++i_) *(LAS u32x4*)(Vs + ((tid >> 6) + 8 * i_) * 1040 + (tid & 63) * 16) = vr[i_]; } while (0)
; __device__ __forceinline__ void ret_unit(ldsp lds, bf16_t* R, const bf16_t* RC, int b, int h, int qblk, float lgf2, float lgb2, const int tid_in) {
;     ...
;     for (int t = 0; t < 36; ++t) {
;         int tl_ = tid_outer; asm volatile("" : "+v"(tl_));
;         const int tid = tl_, lane = tid & 63, l15 = lane & 15, lg = lane >> 4;
;         if (wid < 4) { RET_PV(t); if (t + 1 < 36) RET_S(t + 1, TI(t + 1)); }
;         else { if (t + 1 < 36) RET_S(t + 1, TI(t + 1)); RET_PV(t); }
;         RET_BAR();
;         asm volatile("s_waitcnt vmcnt(0)" ::: "memory");
;         if (t + 1 < 36) RET_STOREV();
;         if (t + 2 < 36) RET_LOADV(TI(t + 2));
;         if (t + 3 < 36) RET_DMAK(TI(t + 3), (t + 1) & 1);
;         RET_BAR();
.Lret_wdone_54:
	v_mul_f32_e32 v170, v98, v166
	v_mul_f32_e32 v171, v99, v167
	v_mul_f32_e32 v172, v100, v168
	v_mul_f32_e32 v173, v101, v169
	v_cvt_pk_bf16_f32 v174, v170, v171
	v_cvt_pk_bf16_f32 v175, v172, v173
	ds_write_b64 v188, v[174:175] offset:0
	s_waitcnt vmcnt(4)
	s_add_i32 s41, s27, 4
	v_readlane_b32 s42, v238, s41
	v_readlane_b32 s43, v239, s41
	v_readlane_b32 s4, v237, s41
	s_mov_b32 s5, s4
	s_nop 0
	v_cndmask_b32_e64 v230, v191, v189, s[4:5]
	v_cndmask_b32_e64 v231, v192, v190, s[4:5]
	v_cndmask_b32_e64 v232, v198, v193, s[4:5]
	v_cndmask_b32_e64 v233, v199, v194, s[4:5]
	v_cndmask_b32_e64 v234, v200, v195, s[4:5]
	v_cndmask_b32_e64 v235, v202, v197, s[4:5]
	s_add_i32 m0, s54, 32768
	s_nop 0
	global_load_lds_dwordx4 v230, s[42:43]
	s_add_i32 m0, s54, 33792
	s_nop 0
	global_load_lds_dwordx4 v231, s[42:43]
	s_add_i32 m0, s55, 8192
	s_nop 0
	global_load_lds_dwordx4 v232, s[42:43]
	s_add_i32 m0, s55, 9216
	s_nop 0
	global_load_lds_dwordx4 v233, s[42:43]
	s_add_i32 m0, s55, 10240
	s_nop 0
	global_load_lds_dwordx4 v234, s[42:43]
	s_add_i32 m0, s55, 11264
	s_nop 0
	global_load_lds_dwordx4 v235, s[42:43]
	ds_read_b64_tr_b16 v[150:151], v183 offset:0
	ds_read_b64_tr_b16 v[152:153], v183 offset:512
	ds_read_b64_tr_b16 v[154:155], v184 offset:0
	ds_read_b64_tr_b16 v[156:157], v184 offset:512
	ds_read_b64_tr_b16 v[158:159], v185 offset:0
	ds_read_b64_tr_b16 v[160:161], v185 offset:512
	ds_read_b64_tr_b16 v[162:163], v186 offset:0
	ds_read_b64_tr_b16 v[164:165], v186 offset:512
	s_waitcnt lgkmcnt(8)
.Lret_regJ_48:
	s_barrier
	s_add_i32 s27, s27, 3
	s_cmp_lt_u32 s27, 33
	s_cbranch_scc1 .Lret_loop
	s_cmp_eq_u32 s38, 0
	s_cbranch_scc0 .Lret_regY_55
	ds_read_b128 v[102:105], v182 offset:16384
	ds_read_b128 v[106:109], v246 offset:16384
	ds_read_b128 v[110:113], v247 offset:16384
	ds_read_b128 v[114:117], v248 offset:16384
	ds_read_b128 v[118:121], v182 offset:16640
	ds_read_b128 v[122:125], v246 offset:16640
	ds_read_b128 v[126:129], v247 offset:16640
	ds_read_b128 v[130:133], v248 offset:16640
	ds_read_b128 v[134:137], v187 offset:0
	ds_read_b128 v[138:141], v187 offset:1280
	ds_read_b128 v[142:145], v187 offset:2560
	ds_read_b128 v[146:149], v187 offset:3840
	s_waitcnt lgkmcnt(11)
	v_mfma_f32_16x16x32_bf16 v[98:101], v[102:105], v[64:67], 0
	s_waitcnt lgkmcnt(10)
	v_mfma_f32_16x16x32_bf16 v[98:101], v[106:109], v[68:71], v[98:101]
	s_waitcnt lgkmcnt(9)
	v_mfma_f32_16x16x32_bf16 v[98:101], v[110:113], v[72:75], v[98:101]
	s_waitcnt lgkmcnt(8)
	v_mfma_f32_16x16x32_bf16 v[98:101], v[114:117], v[76:79], v[98:101]
	s_waitcnt lgkmcnt(7)
	v_mfma_f32_16x16x32_bf16 v[98:101], v[118:121], v[80:83], v[98:101]
	s_waitcnt lgkmcnt(6)
	v_mfma_f32_16x16x32_bf16 v[98:101], v[122:125], v[84:87], v[98:101]
	s_waitcnt lgkmcnt(5)
	v_mfma_f32_16x16x32_bf16 v[98:101], v[126:129], v[88:91], v[98:101]
	s_waitcnt lgkmcnt(4)
	v_mfma_f32_16x16x32_bf16 v[98:101], v[130:133], v[92:95], v[98:101]
	s_waitcnt lgkmcnt(0)
	v_mfma_f32_16x16x32_bf16 v[0:3], v[150:153], v[134:137], v[0:3]
	v_mfma_f32_16x16x32_bf16 v[16:19], v[154:157], v[134:137], v[16:19]
	v_mfma_f32_16x16x32_bf16 v[32:35], v[158:161], v[134:137], v[32:35]
	v_mfma_f32_16x16x32_bf16 v[48:51], v[162:165], v[134:137], v[48:51]
	v_mfma_f32_16x16x32_bf16 v[4:7], v[150:153], v[138:141], v[4:7]
	v_mfma_f32_16x16x32_bf16 v[20:23], v[154:157], v[138:141], v[20:23]
	v_mfma_f32_16x16x32_bf16 v[36:39], v[158:161], v[138:141], v[36:39]
	v_mfma_f32_16x16x32_bf16 v[52:55], v[162:165], v[138:141], v[52:55]
	v_mfma_f32_16x16x32_bf16 v[8:11], v[150:153], v[142:145], v[8:11]
	v_mfma_f32_16x16x32_bf16 v[24:27], v[154:157], v[142:145], v[24:27]
	v_mfma_f32_16x16x32_bf16 v[40:43], v[158:161], v[142:145], v[40:43]
	v_mfma_f32_16x16x32_bf16 v[56:59], v[162:165], v[142:145], v[56:59]
	v_mfma_f32_16x16x32_bf16 v[12:15], v[150:153], v[146:149], v[12:15]
	v_mfma_f32_16x16x32_bf16 v[28:31], v[154:157], v[146:149], v[28:31]
	v_mfma_f32_16x16x32_bf16 v[44:47], v[158:161], v[146:149], v[44:47]
	v_mfma_f32_16x16x32_bf16 v[60:63], v[162:165], v[146:149], v[60:63]
	v_mul_f32_e32 v170, v98, v242
	v_mul_f32_e32 v171, v99, v243
	v_mul_f32_e32 v172, v100, v244
	v_mul_f32_e32 v173, v101, v245
	v_cvt_pk_bf16_f32 v174, v170, v171
	v_cvt_pk_bf16_f32 v175, v172, v173
	ds_write_b64 v188, v[174:175] offset:5120
	s_waitcnt vmcnt(4)
	s_add_i32 s41, s27, 1
	v_readlane_b32 s42, v240, s41
	v_readlane_b32 s43, v241, s41
	v_readlane_b32 s4, v237, s41
	s_mov_b32 s5, s4
	s_nop 0
	v_cndmask_b32_e64 v230, v191, v189, s[4:5]
	v_cndmask_b32_e64 v231, v192, v190, s[4:5]
	v_cndmask_b32_e64 v232, v198, v193, s[4:5]
	v_cndmask_b32_e64 v233, v199, v194, s[4:5]
	v_cndmask_b32_e64 v234, v200, v195, s[4:5]
	v_cndmask_b32_e64 v235, v202, v197, s[4:5]
	s_add_i32 m0, s54, 0
	s_nop 0
	global_load_lds_dwordx4 v230, s[42:43]
	s_add_i32 m0, s54, 1024
	s_nop 0
	global_load_lds_dwordx4 v231, s[42:43]
	s_add_i32 m0, s55, 0
	s_nop 0
	global_load_lds_dwordx4 v232, s[42:43]
	s_add_i32 m0, s55, 1024
	s_nop 0
	global_load_lds_dwordx4 v233, s[42:43]
	s_add_i32 m0, s55, 2048
	s_nop 0
	global_load_lds_dwordx4 v234, s[42:43]
	s_add_i32 m0, s55, 3072
	s_nop 0
	global_load_lds_dwordx4 v235, s[42:43]
	ds_read_b64_tr_b16 v[150:151], v183 offset:4096
	ds_read_b64_tr_b16 v[152:153], v183 offset:4608
	ds_read_b64_tr_b16 v[154:155], v184 offset:4096
	ds_read_b64_tr_b16 v[156:157], v184 offset:4608
	ds_read_b64_tr_b16 v[158:159], v185 offset:4096
	ds_read_b64_tr_b16 v[160:161], v185 offset:4608
	ds_read_b64_tr_b16 v[162:163], v186 offset:4096
	ds_read_b64_tr_b16 v[164:165], v186 offset:4608
	s_add_i32 s41, s27, 1
	v_readlane_b32 s37, v236, s41
	s_cmp_lt_u32 s37, 32
	s_cbranch_scc0 .Lret_wctx_57
	s_lshl_b32 s100, s37, 6
	s_cmp_eq_u32 s37, s9
	s_cbranch_scc1 .Lret_wdiag_58
	s_cmp_lt_u32 s37, s9
	s_cselect_b32 s101, s11, s12
	v_subrev_u32_e32 v170, s100, v203
	v_subrev_u32_e32 v171, s100, v204
	v_subrev_u32_e32 v172, s100, v205
	v_subrev_u32_e32 v173, s100, v206
	v_cvt_f32_i32_e32 v174, v170
	v_cvt_f32_i32_e32 v175, v171
	v_cvt_f32_i32_e32 v176, v172
	v_cvt_f32_i32_e32 v177, v173
	v_mul_f32_e64 v178, s101, |v174|
	v_mul_f32_e64 v179, s101, |v175|
	v_mul_f32_e64 v180, s101, |v176|
	v_mul_f32_e64 v181, s101, |v177|
	v_exp_f32_e32 v166, v178
	v_exp_f32_e32 v167, v179
	v_exp_f32_e32 v168, v180
	v_exp_f32_e32 v169, v181
	s_branch .Lret_wdone_59
